# phase 4a/4b epilogues: gate/t1 loads prefetched (rolling) instead of load-wait(0) per half-row
# speedup vs baseline: 1.0000x; 1.0000x over previous
; __device__ __forceinline__ unsigned pk_bf16(float lo, float hi) { const f32x2 v = {lo, hi}; return __builtin_bit_cast(unsigned, __builtin_convertvector(v, b16x2)); }
;     __device__ __forceinline__ void row(int r, int col32, int fq, const f32x4& a00, const f32x4& a01, const f32x4& a10, const f32x4& a11) const { half(r, col32, fq, a00, a01); half(r, col32 + HALF, fq, a10, a11); }
;     __device__ __forceinline__ void row(int r, int col32, int fq, const f32x4& a00, const f32x4& a01, const f32x4& a10, const f32x4& a11) const { half(r, col32, fq, a00, a01); half(r, col32 + HALF, fq, a10, a11); }
;     ...
;             const int brow = cur.pm * BM, bcol = cur.pn * BM;
; #pragma unroll
;             for (int ai = 0; ai < 2; ++ai)
; #pragma unroll
;                 for (int m = 0; m < 4; ++m) {
;                     E.row(brow + ai * HALF + wr * 64 + m * 16 + fr, bcol + wc * 32, fq, acc[ai][0][m][0], acc[ai][0][m][1], acc[ai][1][m][0], acc[ai][1][m][1]);
;                     asm volatile("" ::: "memory");
;                 }
;     __device__ __forceinline__ void half(int row, int col32, int fq, const f32x4& v0, const f32x4& v1) const {
;         const int col = col32 + 8 * fq;
;         float g[8]; bf8_to_f(*(const u32x4*)(gates + (size_t)row * 2048 + col), g);
;         u32x4 w; w.x = pk_bf16(v0[0] * g[0], v0[1] * g[1]); w.y = pk_bf16(v0[2] * g[2], v0[3] * g[3]); w.z = pk_bf16(v1[0] * g[4], v1[1] * g[5]); w.w = pk_bf16(v1[2] * g[6], v1[3] * g[7]);
;         *(u32x4*)(t1 + (size_t)row * D + col) = w;
;     }
;     __device__ __forceinline__ void row(int r, int col32, int fq, const f32x4& a00, const f32x4& a01, const f32x4& a10, const f32x4& a11) const { half(r, col32, fq, a00, a01); half(r, col32 + HALF, fq, a10, a11); }
.LBB0_1026:
	v_lshl_add_u32 v154, s24, 8, v129
	v_lshl_or_b32 v152, s46, 8, v135
	v_ashrrev_i32_e32 v155, 31, v154
	v_ashrrev_i32_e32 v153, 31, v152
	v_lshlrev_b64 v[176:177], 12, v[154:155]
	v_lshl_add_u64 v[176:177], s[88:89], 0, v[176:177]
	v_lshlrev_b64 v[152:153], 1, v[152:153]
	v_add_u32_e32 v184, 0x0, v154
	v_ashrrev_i32_e32 v185, 31, v184
	v_lshlrev_b64 v[186:187], 12, v[184:185]
	v_lshl_add_u64 v[186:187], s[88:89], 0, v[186:187]
	v_lshl_add_u64 v[186:187], v[186:187], 0, v[152:153]
	global_load_dwordx4 v[188:191], v[186:187], off
	global_load_dwordx4 v[192:195], v[186:187], off offset:256
	s_nop 0
	v_add_u32_e32 v184, 0x10, v154
	v_ashrrev_i32_e32 v185, 31, v184
	v_lshlrev_b64 v[186:187], 12, v[184:185]
	v_lshl_add_u64 v[186:187], s[88:89], 0, v[186:187]
	v_lshl_add_u64 v[186:187], v[186:187], 0, v[152:153]
	global_load_dwordx4 v[196:199], v[186:187], off
	global_load_dwordx4 v[200:203], v[186:187], off offset:256
	s_nop 0
	v_add_u32_e32 v184, 0x20, v154
	v_ashrrev_i32_e32 v185, 31, v184
	v_lshlrev_b64 v[186:187], 12, v[184:185]
	v_lshl_add_u64 v[186:187], s[88:89], 0, v[186:187]
	v_lshl_add_u64 v[186:187], v[186:187], 0, v[152:153]
	global_load_dwordx4 v[204:207], v[186:187], off
	global_load_dwordx4 v[208:211], v[186:187], off offset:256
	s_nop 0
	v_add_u32_e32 v184, 0x30, v154
	v_ashrrev_i32_e32 v185, 31, v184
	v_lshlrev_b64 v[186:187], 12, v[184:185]
	v_lshl_add_u64 v[186:187], s[88:89], 0, v[186:187]
	v_lshl_add_u64 v[186:187], v[186:187], 0, v[152:153]
	global_load_dwordx4 v[212:215], v[186:187], off
	global_load_dwordx4 v[216:219], v[186:187], off offset:256
	s_nop 0
	v_add_u32_e32 v184, 0x80, v154
	v_ashrrev_i32_e32 v185, 31, v184
	v_lshlrev_b64 v[186:187], 12, v[184:185]
	v_lshl_add_u64 v[186:187], s[88:89], 0, v[186:187]
	v_lshl_add_u64 v[186:187], v[186:187], 0, v[152:153]
	global_load_dwordx4 v[220:223], v[186:187], off
	global_load_dwordx4 v[228:231], v[186:187], off offset:256
	s_nop 0
	v_add_u32_e32 v184, 0x90, v154
	v_ashrrev_i32_e32 v185, 31, v184
	v_lshlrev_b64 v[186:187], 12, v[184:185]
	v_lshl_add_u64 v[186:187], s[88:89], 0, v[186:187]
	v_lshl_add_u64 v[186:187], v[186:187], 0, v[152:153]
	global_load_dwordx4 v[232:235], v[186:187], off
	global_load_dwordx4 v[236:239], v[186:187], off offset:256
	s_nop 0
	v_add_u32_e32 v184, 0xa0, v154
	v_ashrrev_i32_e32 v185, 31, v184
	v_lshlrev_b64 v[186:187], 12, v[184:185]
	v_lshl_add_u64 v[186:187], s[88:89], 0, v[186:187]
	v_lshl_add_u64 v[186:187], v[186:187], 0, v[152:153]
	global_load_dwordx4 v[240:243], v[186:187], off
	global_load_dwordx4 v[244:247], v[186:187], off offset:256
	s_nop 0
	v_lshl_add_u64 v[180:181], v[176:177], 0, v[152:153]
	v_lshlrev_b64 v[182:183], 11, v[154:155]
	v_lshl_add_u64 v[182:183], s[8:9], 0, v[182:183]
	v_lshl_add_u64 v[182:183], v[182:183], 0, v[152:153]
	s_andn2_b64 vcc, exec, s[4:5]
	s_mov_b64 s[4:5], -1
	s_waitcnt vmcnt(0)
	v_lshlrev_b32_e32 v184, 16, v188
	v_and_b32_e32 v185, 0xffff0000, v188
	v_lshlrev_b32_e32 v176, 16, v189
	v_and_b32_e32 v177, 0xffff0000, v189
	v_lshlrev_b32_e32 v186, 16, v190
	v_and_b32_e32 v187, 0xffff0000, v190
	v_lshlrev_b32_e32 v178, 16, v191
	v_and_b32_e32 v179, 0xffff0000, v191
	v_pk_mul_f32 v[124:125], v[124:125], v[184:185]
	v_pk_mul_f32 v[126:127], v[126:127], v[176:177]
	v_pk_mul_f32 v[176:177], v[120:121], v[186:187]
	v_pk_mul_f32 v[178:179], v[122:123], v[178:179]
	v_cvt_pk_bf16_f32 v120, v124, v125
	v_cvt_pk_bf16_f32 v121, v126, v127
	v_cvt_pk_bf16_f32 v122, v176, v177
	v_cvt_pk_bf16_f32 v123, v178, v179
	global_store_dwordx4 v[182:183], v[120:123], off
	v_or_b32_e32 v124, 16, v154
	v_ashrrev_i32_e32 v125, 31, v124
	v_lshlrev_b64 v[126:127], 12, v[124:125]
	v_lshl_add_u64 v[126:127], s[88:89], 0, v[126:127]
	v_lshl_add_u64 v[126:127], v[126:127], 0, v[152:153]
	v_lshlrev_b32_e32 v176, 16, v192
	v_and_b32_e32 v177, 0xffff0000, v192
	v_lshlrev_b32_e32 v120, 16, v193
	v_and_b32_e32 v121, 0xffff0000, v193
	v_lshlrev_b32_e32 v178, 16, v194
	v_and_b32_e32 v179, 0xffff0000, v194
	v_lshlrev_b32_e32 v122, 16, v195
	v_and_b32_e32 v123, 0xffff0000, v195
	v_add_u32_e32 v184, 0xb0, v154
	v_ashrrev_i32_e32 v185, 31, v184
	v_lshlrev_b64 v[186:187], 12, v[184:185]
	v_lshl_add_u64 v[186:187], s[88:89], 0, v[186:187]
	v_lshl_add_u64 v[186:187], v[186:187], 0, v[152:153]
	global_load_dwordx4 v[188:191], v[186:187], off
	global_load_dwordx4 v[192:195], v[186:187], off offset:256
	s_nop 0
	v_pk_mul_f32 v[116:117], v[116:117], v[176:177]
	v_pk_mul_f32 v[118:119], v[118:119], v[120:121]
	v_pk_mul_f32 v[120:121], v[112:113], v[178:179]
	v_pk_mul_f32 v[122:123], v[114:115], v[122:123]
	v_cvt_pk_bf16_f32 v112, v116, v117
	v_cvt_pk_bf16_f32 v113, v118, v119
	v_cvt_pk_bf16_f32 v114, v120, v121
	v_cvt_pk_bf16_f32 v115, v122, v123
	global_store_dwordx4 v[182:183], v[112:115], off offset:256
	v_lshlrev_b64 v[116:117], 11, v[124:125]
	v_lshl_add_u64 v[116:117], s[8:9], 0, v[116:117]
	v_lshl_add_u64 v[116:117], v[116:117], 0, v[152:153]
	v_lshlrev_b32_e32 v118, 16, v196
	v_and_b32_e32 v119, 0xffff0000, v196
	v_lshlrev_b32_e32 v112, 16, v197
	v_and_b32_e32 v113, 0xffff0000, v197
	v_lshlrev_b32_e32 v120, 16, v198
	v_and_b32_e32 v121, 0xffff0000, v198
	v_lshlrev_b32_e32 v114, 16, v199
	v_and_b32_e32 v115, 0xffff0000, v199
	v_pk_mul_f32 v[108:109], v[108:109], v[118:119]
	v_pk_mul_f32 v[110:111], v[110:111], v[112:113]
	v_pk_mul_f32 v[112:113], v[104:105], v[120:121]
	v_pk_mul_f32 v[114:115], v[106:107], v[114:115]
	v_cvt_pk_bf16_f32 v104, v108, v109
	v_cvt_pk_bf16_f32 v105, v110, v111
	v_cvt_pk_bf16_f32 v106, v112, v113
	v_cvt_pk_bf16_f32 v107, v114, v115
	global_store_dwordx4 v[116:117], v[104:107], off
	v_or_b32_e32 v108, 32, v154
; __device__ __forceinline__ unsigned pk_bf16(float lo, float hi) { const f32x2 v = {lo, hi}; return __builtin_bit_cast(unsigned, __builtin_convertvector(v, b16x2)); }
;     __device__ __forceinline__ void row(int r, int col32, int fq, const f32x4& a00, const f32x4& a01, const f32x4& a10, const f32x4& a11) const { half(r, col32, fq, a00, a01); half(r, col32 + HALF, fq, a10, a11); }
;     __device__ __forceinline__ void row(int r, int col32, int fq, const f32x4& a00, const f32x4& a01, const f32x4& a10, const f32x4& a11) const { half(r, col32, fq, a00, a01); half(r, col32 + HALF, fq, a10, a11); }
;     ...
;             const int brow = cur.pm * BM, bcol = cur.pn * BM;
; #pragma unroll
;             for (int ai = 0; ai < 2; ++ai)
; #pragma unroll
;                 for (int m = 0; m < 4; ++m) {
;                     E.row(brow + ai * HALF + wr * 64 + m * 16 + fr, bcol + wc * 32, fq, acc[ai][0][m][0], acc[ai][0][m][1], acc[ai][1][m][0], acc[ai][1][m][1]);
;                     asm volatile("" ::: "memory");
;                 }
;     __device__ __forceinline__ void half(int row, int col32, int fq, const f32x4& v0, const f32x4& v1) const {
;         const int col = col32 + 8 * fq;
;         float g[8]; bf8_to_f(*(const u32x4*)(gates + (size_t)row * 2048 + col), g);
;         u32x4 w; w.x = pk_bf16(v0[0] * g[0], v0[1] * g[1]); w.y = pk_bf16(v0[2] * g[2], v0[3] * g[3]); w.z = pk_bf16(v1[0] * g[4], v1[1] * g[5]); w.w = pk_bf16(v1[2] * g[6], v1[3] * g[7]);
;         *(u32x4*)(t1 + (size_t)row * D + col) = w;
;     }
;     __device__ __forceinline__ void row(int r, int col32, int fq, const f32x4& a00, const f32x4& a01, const f32x4& a10, const f32x4& a11) const { half(r, col32, fq, a00, a01); half(r, col32 + HALF, fq, a10, a11); }
	v_ashrrev_i32_e32 v109, 31, v108
	v_lshlrev_b64 v[110:111], 12, v[108:109]
	v_lshl_add_u64 v[110:111], s[88:89], 0, v[110:111]
	v_lshl_add_u64 v[110:111], v[110:111], 0, v[152:153]
	v_lshlrev_b32_e32 v112, 16, v200
	v_and_b32_e32 v113, 0xffff0000, v200
	v_lshlrev_b32_e32 v104, 16, v201
	v_and_b32_e32 v105, 0xffff0000, v201
	v_lshlrev_b32_e32 v114, 16, v202
	v_and_b32_e32 v115, 0xffff0000, v202
	v_lshlrev_b32_e32 v106, 16, v203
	v_and_b32_e32 v107, 0xffff0000, v203
	v_pk_mul_f32 v[100:101], v[100:101], v[112:113]
	v_pk_mul_f32 v[102:103], v[102:103], v[104:105]
	v_pk_mul_f32 v[104:105], v[96:97], v[114:115]
	v_pk_mul_f32 v[106:107], v[98:99], v[106:107]
	v_cvt_pk_bf16_f32 v96, v100, v101
	v_cvt_pk_bf16_f32 v97, v102, v103
	v_cvt_pk_bf16_f32 v98, v104, v105
	v_cvt_pk_bf16_f32 v99, v106, v107
	global_store_dwordx4 v[116:117], v[96:99], off offset:256
	v_lshlrev_b64 v[100:101], 11, v[108:109]
	v_lshl_add_u64 v[100:101], s[8:9], 0, v[100:101]
	v_lshl_add_u64 v[100:101], v[100:101], 0, v[152:153]
	v_lshlrev_b32_e32 v102, 16, v204
	v_and_b32_e32 v103, 0xffff0000, v204
	v_lshlrev_b32_e32 v96, 16, v205
	v_and_b32_e32 v97, 0xffff0000, v205
	v_lshlrev_b32_e32 v104, 16, v206
	v_and_b32_e32 v105, 0xffff0000, v206
	v_lshlrev_b32_e32 v98, 16, v207
	v_and_b32_e32 v99, 0xffff0000, v207
	v_pk_mul_f32 v[92:93], v[92:93], v[102:103]
	v_pk_mul_f32 v[94:95], v[94:95], v[96:97]
	v_pk_mul_f32 v[96:97], v[88:89], v[104:105]
	v_pk_mul_f32 v[98:99], v[90:91], v[98:99]
	v_cvt_pk_bf16_f32 v88, v92, v93
	v_cvt_pk_bf16_f32 v89, v94, v95
	v_cvt_pk_bf16_f32 v90, v96, v97
	v_cvt_pk_bf16_f32 v91, v98, v99
	global_store_dwordx4 v[100:101], v[88:91], off
	v_or_b32_e32 v92, 48, v154
	v_ashrrev_i32_e32 v93, 31, v92
	v_lshlrev_b64 v[94:95], 12, v[92:93]
	v_lshl_add_u64 v[94:95], s[88:89], 0, v[94:95]
	v_lshl_add_u64 v[94:95], v[94:95], 0, v[152:153]
	v_lshlrev_b32_e32 v96, 16, v208
	v_and_b32_e32 v97, 0xffff0000, v208
	v_lshlrev_b32_e32 v88, 16, v209
	v_and_b32_e32 v89, 0xffff0000, v209
	v_lshlrev_b32_e32 v98, 16, v210
	v_and_b32_e32 v99, 0xffff0000, v210
	v_lshlrev_b32_e32 v90, 16, v211
	v_and_b32_e32 v91, 0xffff0000, v211
	v_pk_mul_f32 v[84:85], v[84:85], v[96:97]
	v_pk_mul_f32 v[86:87], v[86:87], v[88:89]
	v_pk_mul_f32 v[88:89], v[80:81], v[98:99]
	v_pk_mul_f32 v[90:91], v[82:83], v[90:91]
	v_cvt_pk_bf16_f32 v80, v84, v85
	v_cvt_pk_bf16_f32 v81, v86, v87
	v_cvt_pk_bf16_f32 v82, v88, v89
	v_cvt_pk_bf16_f32 v83, v90, v91
	global_store_dwordx4 v[100:101], v[80:83], off offset:256
	v_lshlrev_b64 v[84:85], 11, v[92:93]
	v_lshl_add_u64 v[84:85], s[8:9], 0, v[84:85]
	v_lshl_add_u64 v[84:85], v[84:85], 0, v[152:153]
	v_lshlrev_b32_e32 v86, 16, v212
	v_and_b32_e32 v87, 0xffff0000, v212
	v_lshlrev_b32_e32 v80, 16, v213
	v_and_b32_e32 v81, 0xffff0000, v213
	v_lshlrev_b32_e32 v88, 16, v214
	v_and_b32_e32 v89, 0xffff0000, v214
	v_lshlrev_b32_e32 v82, 16, v215
	v_and_b32_e32 v83, 0xffff0000, v215
	v_pk_mul_f32 v[76:77], v[76:77], v[86:87]
	v_pk_mul_f32 v[78:79], v[78:79], v[80:81]
	v_pk_mul_f32 v[80:81], v[72:73], v[88:89]
	v_pk_mul_f32 v[82:83], v[74:75], v[82:83]
	v_cvt_pk_bf16_f32 v72, v76, v77
	v_cvt_pk_bf16_f32 v73, v78, v79
	v_cvt_pk_bf16_f32 v74, v80, v81
	v_cvt_pk_bf16_f32 v75, v82, v83
	global_store_dwordx4 v[84:85], v[72:75], off
	v_add_u32_e32 v76, 0x80, v154
	v_ashrrev_i32_e32 v77, 31, v76
	v_lshlrev_b64 v[78:79], 12, v[76:77]
	v_lshl_add_u64 v[78:79], s[88:89], 0, v[78:79]
	v_lshl_add_u64 v[78:79], v[78:79], 0, v[152:153]
	v_lshlrev_b32_e32 v80, 16, v216
	v_and_b32_e32 v81, 0xffff0000, v216
	v_lshlrev_b32_e32 v72, 16, v217
	v_and_b32_e32 v73, 0xffff0000, v217
	v_lshlrev_b32_e32 v82, 16, v218
	v_and_b32_e32 v83, 0xffff0000, v218
	v_lshlrev_b32_e32 v74, 16, v219
	v_and_b32_e32 v75, 0xffff0000, v219
	v_pk_mul_f32 v[68:69], v[68:69], v[80:81]
	v_pk_mul_f32 v[70:71], v[70:71], v[72:73]
	v_pk_mul_f32 v[72:73], v[64:65], v[82:83]
	v_pk_mul_f32 v[74:75], v[66:67], v[74:75]
	v_cvt_pk_bf16_f32 v64, v68, v69
	v_cvt_pk_bf16_f32 v65, v70, v71
	v_cvt_pk_bf16_f32 v66, v72, v73
	v_cvt_pk_bf16_f32 v67, v74, v75
	global_store_dwordx4 v[84:85], v[64:67], off offset:256
	v_lshlrev_b64 v[68:69], 11, v[76:77]
	v_lshl_add_u64 v[68:69], s[8:9], 0, v[68:69]
	v_lshl_add_u64 v[68:69], v[68:69], 0, v[152:153]
	v_lshlrev_b32_e32 v70, 16, v220
	v_and_b32_e32 v71, 0xffff0000, v220
	v_lshlrev_b32_e32 v64, 16, v221
	v_and_b32_e32 v65, 0xffff0000, v221
	v_lshlrev_b32_e32 v72, 16, v222
	v_and_b32_e32 v73, 0xffff0000, v222
	v_lshlrev_b32_e32 v66, 16, v223
	v_and_b32_e32 v67, 0xffff0000, v223
	v_pk_mul_f32 v[60:61], v[60:61], v[70:71]
	v_pk_mul_f32 v[62:63], v[62:63], v[64:65]
	v_pk_mul_f32 v[64:65], v[56:57], v[72:73]
	v_pk_mul_f32 v[66:67], v[58:59], v[66:67]
	v_cvt_pk_bf16_f32 v56, v60, v61
	v_cvt_pk_bf16_f32 v57, v62, v63
	v_cvt_pk_bf16_f32 v58, v64, v65
	v_cvt_pk_bf16_f32 v59, v66, v67
	global_store_dwordx4 v[68:69], v[56:59], off
	v_add_u32_e32 v60, 0x90, v154
	v_ashrrev_i32_e32 v61, 31, v60
	v_lshlrev_b64 v[62:63], 12, v[60:61]
	v_lshl_add_u64 v[62:63], s[88:89], 0, v[62:63]
	v_lshl_add_u64 v[62:63], v[62:63], 0, v[152:153]
	v_lshlrev_b32_e32 v64, 16, v228
	v_and_b32_e32 v65, 0xffff0000, v228
	v_lshlrev_b32_e32 v56, 16, v229
	v_and_b32_e32 v57, 0xffff0000, v229
; __device__ __forceinline__ unsigned pk_bf16(float lo, float hi) { const f32x2 v = {lo, hi}; return __builtin_bit_cast(unsigned, __builtin_convertvector(v, b16x2)); }
;     __device__ __forceinline__ void row(int r, int col32, int fq, const f32x4& a00, const f32x4& a01, const f32x4& a10, const f32x4& a11) const { half(r, col32, fq, a00, a01); half(r, col32 + HALF, fq, a10, a11); }
;     __device__ __forceinline__ void row(int r, int col32, int fq, const f32x4& a00, const f32x4& a01, const f32x4& a10, const f32x4& a11) const { half(r, col32, fq, a00, a01); half(r, col32 + HALF, fq, a10, a11); }
;     ...
;             const int brow = cur.pm * BM, bcol = cur.pn * BM;
; #pragma unroll
;             for (int ai = 0; ai < 2; ++ai)
; #pragma unroll
;                 for (int m = 0; m < 4; ++m) {
;                     E.row(brow + ai * HALF + wr * 64 + m * 16 + fr, bcol + wc * 32, fq, acc[ai][0][m][0], acc[ai][0][m][1], acc[ai][1][m][0], acc[ai][1][m][1]);
;                     asm volatile("" ::: "memory");
;                 }
;     __device__ __forceinline__ void half(int row, int col32, int fq, const f32x4& v0, const f32x4& v1) const {
;         const int col = col32 + 8 * fq;
;         float g[8]; bf8_to_f(*(const u32x4*)(gates + (size_t)row * 2048 + col), g);
;         u32x4 w; w.x = pk_bf16(v0[0] * g[0], v0[1] * g[1]); w.y = pk_bf16(v0[2] * g[2], v0[3] * g[3]); w.z = pk_bf16(v1[0] * g[4], v1[1] * g[5]); w.w = pk_bf16(v1[2] * g[6], v1[3] * g[7]);
;         *(u32x4*)(t1 + (size_t)row * D + col) = w;
;     }
;     __device__ __forceinline__ void row(int r, int col32, int fq, const f32x4& a00, const f32x4& a01, const f32x4& a10, const f32x4& a11) const { half(r, col32, fq, a00, a01); half(r, col32 + HALF, fq, a10, a11); }
	v_lshlrev_b32_e32 v66, 16, v230
	v_and_b32_e32 v67, 0xffff0000, v230
	v_lshlrev_b32_e32 v58, 16, v231
	v_and_b32_e32 v59, 0xffff0000, v231
	v_pk_mul_f32 v[52:53], v[52:53], v[64:65]
	v_pk_mul_f32 v[54:55], v[54:55], v[56:57]
	v_pk_mul_f32 v[56:57], v[48:49], v[66:67]
	v_pk_mul_f32 v[58:59], v[50:51], v[58:59]
	v_cvt_pk_bf16_f32 v48, v52, v53
	v_cvt_pk_bf16_f32 v49, v54, v55
	v_cvt_pk_bf16_f32 v50, v56, v57
	v_cvt_pk_bf16_f32 v51, v58, v59
	global_store_dwordx4 v[68:69], v[48:51], off offset:256
	v_lshlrev_b64 v[52:53], 11, v[60:61]
	v_lshl_add_u64 v[52:53], s[8:9], 0, v[52:53]
	v_lshl_add_u64 v[52:53], v[52:53], 0, v[152:153]
	v_lshlrev_b32_e32 v54, 16, v232
	v_and_b32_e32 v55, 0xffff0000, v232
	v_lshlrev_b32_e32 v48, 16, v233
	v_and_b32_e32 v49, 0xffff0000, v233
	v_lshlrev_b32_e32 v56, 16, v234
	v_and_b32_e32 v57, 0xffff0000, v234
	v_lshlrev_b32_e32 v50, 16, v235
	v_and_b32_e32 v51, 0xffff0000, v235
	v_pk_mul_f32 v[44:45], v[44:45], v[54:55]
	v_pk_mul_f32 v[46:47], v[46:47], v[48:49]
	v_pk_mul_f32 v[48:49], v[40:41], v[56:57]
	v_pk_mul_f32 v[50:51], v[42:43], v[50:51]
	v_cvt_pk_bf16_f32 v40, v44, v45
	v_cvt_pk_bf16_f32 v41, v46, v47
	v_cvt_pk_bf16_f32 v42, v48, v49
	v_cvt_pk_bf16_f32 v43, v50, v51
	global_store_dwordx4 v[52:53], v[40:43], off
	v_add_u32_e32 v44, 0xa0, v154
	v_ashrrev_i32_e32 v45, 31, v44
	v_lshlrev_b64 v[46:47], 12, v[44:45]
	v_lshl_add_u64 v[46:47], s[88:89], 0, v[46:47]
	v_lshl_add_u64 v[46:47], v[46:47], 0, v[152:153]
	v_lshlrev_b32_e32 v48, 16, v236
	v_and_b32_e32 v49, 0xffff0000, v236
	v_lshlrev_b32_e32 v40, 16, v237
	v_and_b32_e32 v41, 0xffff0000, v237
	v_lshlrev_b32_e32 v50, 16, v238
	v_and_b32_e32 v51, 0xffff0000, v238
	v_lshlrev_b32_e32 v42, 16, v239
	v_and_b32_e32 v43, 0xffff0000, v239
	v_pk_mul_f32 v[36:37], v[36:37], v[48:49]
	v_pk_mul_f32 v[38:39], v[38:39], v[40:41]
	v_pk_mul_f32 v[40:41], v[32:33], v[50:51]
	v_pk_mul_f32 v[42:43], v[34:35], v[42:43]
	v_cvt_pk_bf16_f32 v32, v36, v37
	v_cvt_pk_bf16_f32 v33, v38, v39
	v_cvt_pk_bf16_f32 v34, v40, v41
	v_cvt_pk_bf16_f32 v35, v42, v43
	global_store_dwordx4 v[52:53], v[32:35], off offset:256
	v_lshlrev_b64 v[36:37], 11, v[44:45]
	v_lshl_add_u64 v[36:37], s[8:9], 0, v[36:37]
	v_lshl_add_u64 v[36:37], v[36:37], 0, v[152:153]
	v_lshlrev_b32_e32 v38, 16, v240
	v_and_b32_e32 v39, 0xffff0000, v240
	v_lshlrev_b32_e32 v32, 16, v241
	v_and_b32_e32 v33, 0xffff0000, v241
	v_lshlrev_b32_e32 v40, 16, v242
	v_and_b32_e32 v41, 0xffff0000, v242
	v_lshlrev_b32_e32 v34, 16, v243
	v_and_b32_e32 v35, 0xffff0000, v243
	v_pk_mul_f32 v[28:29], v[28:29], v[38:39]
	v_pk_mul_f32 v[30:31], v[30:31], v[32:33]
	v_pk_mul_f32 v[32:33], v[24:25], v[40:41]
	v_pk_mul_f32 v[34:35], v[26:27], v[34:35]
	v_cvt_pk_bf16_f32 v24, v28, v29
	v_cvt_pk_bf16_f32 v25, v30, v31
	v_cvt_pk_bf16_f32 v26, v32, v33
	v_cvt_pk_bf16_f32 v27, v34, v35
	global_store_dwordx4 v[36:37], v[24:27], off
	v_add_u32_e32 v28, 0xb0, v154
	v_ashrrev_i32_e32 v29, 31, v28
	v_lshlrev_b64 v[30:31], 12, v[28:29]
	v_lshl_add_u64 v[30:31], s[88:89], 0, v[30:31]
	v_lshl_add_u64 v[30:31], v[30:31], 0, v[152:153]
	v_lshlrev_b32_e32 v32, 16, v244
	v_and_b32_e32 v33, 0xffff0000, v244
	v_lshlrev_b32_e32 v24, 16, v245
	v_and_b32_e32 v25, 0xffff0000, v245
	v_lshlrev_b32_e32 v34, 16, v246
	v_and_b32_e32 v35, 0xffff0000, v246
	v_lshlrev_b32_e32 v26, 16, v247
	v_and_b32_e32 v27, 0xffff0000, v247
	v_pk_mul_f32 v[20:21], v[20:21], v[32:33]
	v_pk_mul_f32 v[22:23], v[22:23], v[24:25]
	v_pk_mul_f32 v[24:25], v[16:17], v[34:35]
	v_pk_mul_f32 v[26:27], v[18:19], v[26:27]
	v_cvt_pk_bf16_f32 v16, v20, v21
	v_cvt_pk_bf16_f32 v17, v22, v23
	v_cvt_pk_bf16_f32 v18, v24, v25
	v_cvt_pk_bf16_f32 v19, v26, v27
	global_store_dwordx4 v[36:37], v[16:19], off offset:256
	v_lshlrev_b64 v[20:21], 11, v[28:29]
	v_lshl_add_u64 v[20:21], s[8:9], 0, v[20:21]
	v_lshl_add_u64 v[20:21], v[20:21], 0, v[152:153]
	s_waitcnt vmcnt(13)
	v_lshlrev_b32_e32 v22, 16, v188
	v_and_b32_e32 v23, 0xffff0000, v188
	v_lshlrev_b32_e32 v16, 16, v189
	v_and_b32_e32 v17, 0xffff0000, v189
	v_lshlrev_b32_e32 v24, 16, v190
	v_and_b32_e32 v25, 0xffff0000, v190
	v_lshlrev_b32_e32 v18, 16, v191
	v_and_b32_e32 v19, 0xffff0000, v191
	v_pk_mul_f32 v[12:13], v[12:13], v[22:23]
	v_pk_mul_f32 v[14:15], v[14:15], v[16:17]
	v_pk_mul_f32 v[16:17], v[8:9], v[24:25]
	v_pk_mul_f32 v[18:19], v[10:11], v[18:19]
	v_cvt_pk_bf16_f32 v8, v12, v13
	v_cvt_pk_bf16_f32 v9, v14, v15
	v_cvt_pk_bf16_f32 v10, v16, v17
	v_cvt_pk_bf16_f32 v11, v18, v19
	global_store_dwordx4 v[20:21], v[8:11], off
	v_lshlrev_b32_e32 v12, 16, v192
	v_and_b32_e32 v13, 0xffff0000, v192
	v_lshlrev_b32_e32 v8, 16, v193
	v_and_b32_e32 v9, 0xffff0000, v193
	v_lshlrev_b32_e32 v14, 16, v194
	v_and_b32_e32 v15, 0xffff0000, v194
	v_lshlrev_b32_e32 v10, 16, v195
	v_and_b32_e32 v11, 0xffff0000, v195
	v_pk_mul_f32 v[4:5], v[4:5], v[12:13]
	v_pk_mul_f32 v[6:7], v[6:7], v[8:9]
	v_pk_mul_f32 v[8:9], v[0:1], v[14:15]
	v_pk_mul_f32 v[10:11], v[2:3], v[10:11]
	v_cvt_pk_bf16_f32 v0, v4, v5
	v_cvt_pk_bf16_f32 v1, v6, v7
	v_cvt_pk_bf16_f32 v2, v8, v9
	v_cvt_pk_bf16_f32 v3, v10, v11
	global_store_dwordx4 v[20:21], v[0:3], off offset:256
	s_cbranch_vccnz .LBB0_1015
	s_andn2_b64 vcc, exec, s[6:7]
	s_cbranch_vccnz .LBB0_1014
	s_barrier
	s_branch .LBB0_1014

; __device__ __forceinline__ unsigned pk_bf16(float lo, float hi) { const f32x2 v = {lo, hi}; return __builtin_bit_cast(unsigned, __builtin_convertvector(v, b16x2)); }
;     __device__ __forceinline__ void row(int r, int col32, int fq, const f32x4& a00, const f32x4& a01, const f32x4& a10, const f32x4& a11) const { half(r, col32, fq, a00, a01); half(r, col32 + HALF, fq, a10, a11); }
;     __device__ __forceinline__ void row(int r, int col32, int fq, const f32x4& a00, const f32x4& a01, const f32x4& a10, const f32x4& a11) const { half(r, col32, fq, a00, a01); half(r, col32 + HALF, fq, a10, a11); }
;     ...
;             const int brow = cur.pm * BM, bcol = cur.pn * BM;
; #pragma unroll
;             for (int ai = 0; ai < 2; ++ai)
; #pragma unroll
;                 for (int m = 0; m < 4; ++m) {
;                     E.row(brow + ai * HALF + wr * 64 + m * 16 + fr, bcol + wc * 32, fq, acc[ai][0][m][0], acc[ai][0][m][1], acc[ai][1][m][0], acc[ai][1][m][1]);
;                     asm volatile("" ::: "memory");
;                 }
;     __device__ __forceinline__ void half(int row, int col32, int fq, const f32x4& v0, const f32x4& v1) const {
;         const int col = col32 + 8 * fq;
;         float g[8], a[8]; bf8_to_f(*(const u32x4*)(gates + (size_t)row * 2048 + 1024 + col), g); bf8_to_f(*(const u32x4*)(t1 + (size_t)row * D + col), a);
;         u32x4 w; w.x = pk_bf16(a[0] + v0[0] * g[0], a[1] + v0[1] * g[1]); w.y = pk_bf16(a[2] + v0[2] * g[2], a[3] + v0[3] * g[3]);
;         w.z = pk_bf16(a[4] + v1[0] * g[4], a[5] + v1[1] * g[5]); w.w = pk_bf16(a[6] + v1[2] * g[6], a[7] + v1[3] * g[7]);
;         *(u32x4*)(m + (size_t)row * D + col) = w;
;     }
;     __device__ __forceinline__ void row(int r, int col32, int fq, const f32x4& a00, const f32x4& a01, const f32x4& a10, const f32x4& a11) const { half(r, col32, fq, a00, a01); half(r, col32 + HALF, fq, a10, a11); }
.LBB0_1050:
	v_lshl_add_u32 v154, s26, 8, v129
	v_lshl_or_b32 v152, s46, 8, v135
	v_ashrrev_i32_e32 v155, 31, v154
	v_ashrrev_i32_e32 v153, 31, v152
	v_lshlrev_b64 v[176:177], 12, v[154:155]
	v_lshlrev_b64 v[184:185], 11, v[154:155]
	v_lshl_add_u64 v[176:177], s[88:89], 0, v[176:177]
	v_lshlrev_b64 v[152:153], 1, v[152:153]
	v_add_u32_e32 v236, 0x0, v154
	v_ashrrev_i32_e32 v237, 31, v236
	v_lshlrev_b64 v[238:239], 12, v[236:237]
	v_lshlrev_b64 v[240:241], 11, v[236:237]
	v_lshl_add_u64 v[238:239], s[88:89], 0, v[238:239]
	v_lshl_add_u64 v[240:241], s[8:9], 0, v[240:241]
	v_lshl_add_u64 v[238:239], v[238:239], 0, v[152:153]
	v_lshl_add_u64 v[240:241], v[240:241], 0, v[152:153]
	global_load_dwordx4 v[200:203], v[238:239], off offset:2048
	global_load_dwordx4 v[204:207], v[240:241], off
	global_load_dwordx4 v[208:211], v[240:241], off offset:256
	global_load_dwordx4 v[212:215], v[238:239], off offset:2304
	s_nop 0
	v_add_u32_e32 v236, 0x10, v154
	v_ashrrev_i32_e32 v237, 31, v236
	v_lshlrev_b64 v[238:239], 12, v[236:237]
	v_lshlrev_b64 v[240:241], 11, v[236:237]
	v_lshl_add_u64 v[238:239], s[88:89], 0, v[238:239]
	v_lshl_add_u64 v[240:241], s[8:9], 0, v[240:241]
	v_lshl_add_u64 v[238:239], v[238:239], 0, v[152:153]
	v_lshl_add_u64 v[240:241], v[240:241], 0, v[152:153]
	global_load_dwordx4 v[216:219], v[238:239], off offset:2048
	global_load_dwordx4 v[220:223], v[240:241], off
	global_load_dwordx4 v[228:231], v[240:241], off offset:256
	global_load_dwordx4 v[232:235], v[238:239], off offset:2304
	s_nop 0
	v_lshl_add_u64 v[180:181], s[8:9], 0, v[184:185]
	v_lshl_add_u64 v[188:189], v[176:177], 0, v[152:153]
	v_lshl_add_u64 v[186:187], v[180:181], 0, v[152:153]
	v_lshl_add_u64 v[184:185], s[10:11], 0, v[184:185]
	v_lshl_add_u64 v[190:191], v[184:185], 0, v[152:153]
	s_andn2_b64 vcc, exec, s[6:7]
	s_mov_b64 s[6:7], -1
	s_waitcnt vmcnt(7)
	v_lshlrev_b32_e32 v192, 16, v200
	v_and_b32_e32 v193, 0xffff0000, v200
	s_waitcnt vmcnt(6)
	v_lshlrev_b32_e32 v194, 16, v204
	v_and_b32_e32 v195, 0xffff0000, v204
	v_lshlrev_b32_e32 v176, 16, v201
	v_and_b32_e32 v177, 0xffff0000, v201
	v_lshlrev_b32_e32 v180, 16, v205
	v_and_b32_e32 v181, 0xffff0000, v205
	v_lshlrev_b32_e32 v196, 16, v202
	v_and_b32_e32 v197, 0xffff0000, v202
	v_lshlrev_b32_e32 v198, 16, v206
	v_and_b32_e32 v199, 0xffff0000, v206
	v_lshlrev_b32_e32 v178, 16, v203
	v_and_b32_e32 v179, 0xffff0000, v203
	v_lshlrev_b32_e32 v182, 16, v207
	v_and_b32_e32 v183, 0xffff0000, v207
	v_pk_fma_f32 v[124:125], v[124:125], v[192:193], v[194:195]
	v_pk_fma_f32 v[126:127], v[126:127], v[176:177], v[180:181]
	v_pk_fma_f32 v[176:177], v[120:121], v[196:197], v[198:199]
	v_pk_fma_f32 v[178:179], v[122:123], v[178:179], v[182:183]
	v_cvt_pk_bf16_f32 v120, v124, v125
	v_cvt_pk_bf16_f32 v121, v126, v127
	v_cvt_pk_bf16_f32 v122, v176, v177
	v_cvt_pk_bf16_f32 v123, v178, v179
	global_store_dwordx4 v[190:191], v[120:123], off
	v_or_b32_e32 v124, 16, v154
	s_waitcnt vmcnt(6)
	v_lshlrev_b32_e32 v178, 16, v208
	v_and_b32_e32 v179, 0xffff0000, v208
	v_lshlrev_b32_e32 v180, 16, v209
	v_and_b32_e32 v181, 0xffff0000, v209
	v_lshlrev_b32_e32 v182, 16, v210
	v_and_b32_e32 v183, 0xffff0000, v210
	v_lshlrev_b32_e32 v184, 16, v211
	v_and_b32_e32 v185, 0xffff0000, v211
	v_ashrrev_i32_e32 v125, 31, v124
	v_lshlrev_b64 v[126:127], 12, v[124:125]
	v_lshlrev_b64 v[124:125], 11, v[124:125]
	v_lshl_add_u64 v[126:127], s[88:89], 0, v[126:127]
	v_lshl_add_u64 v[176:177], s[8:9], 0, v[124:125]
	v_lshl_add_u64 v[126:127], v[126:127], 0, v[152:153]
	s_waitcnt vmcnt(5)
	v_lshlrev_b32_e32 v186, 16, v212
	v_and_b32_e32 v187, 0xffff0000, v212
	v_lshlrev_b32_e32 v120, 16, v213
	v_and_b32_e32 v121, 0xffff0000, v213
	v_lshlrev_b32_e32 v188, 16, v214
	v_and_b32_e32 v189, 0xffff0000, v214
	v_lshlrev_b32_e32 v122, 16, v215
	v_and_b32_e32 v123, 0xffff0000, v215
	v_add_u32_e32 v236, 0x20, v154
	v_ashrrev_i32_e32 v237, 31, v236
	v_lshlrev_b64 v[238:239], 12, v[236:237]
	v_lshlrev_b64 v[240:241], 11, v[236:237]
	v_lshl_add_u64 v[238:239], s[88:89], 0, v[238:239]
	v_lshl_add_u64 v[240:241], s[8:9], 0, v[240:241]
	v_lshl_add_u64 v[238:239], v[238:239], 0, v[152:153]
	v_lshl_add_u64 v[240:241], v[240:241], 0, v[152:153]
	global_load_dwordx4 v[200:203], v[238:239], off offset:2048
	global_load_dwordx4 v[204:207], v[240:241], off
	global_load_dwordx4 v[208:211], v[240:241], off offset:256
	global_load_dwordx4 v[212:215], v[238:239], off offset:2304
	s_nop 0
	v_pk_fma_f32 v[116:117], v[116:117], v[186:187], v[178:179]
	v_pk_fma_f32 v[118:119], v[118:119], v[120:121], v[180:181]
	v_pk_fma_f32 v[120:121], v[112:113], v[188:189], v[182:183]
	v_pk_fma_f32 v[122:123], v[114:115], v[122:123], v[184:185]
	v_cvt_pk_bf16_f32 v112, v116, v117
	v_cvt_pk_bf16_f32 v113, v118, v119
	v_cvt_pk_bf16_f32 v114, v120, v121
	v_cvt_pk_bf16_f32 v115, v122, v123
	global_store_dwordx4 v[190:191], v[112:115], off offset:256
	v_lshl_add_u64 v[120:121], v[176:177], 0, v[152:153]
	v_lshl_add_u64 v[122:123], s[10:11], 0, v[124:125]
	v_lshl_add_u64 v[124:125], v[122:123], 0, v[152:153]
	s_waitcnt vmcnt(9)
	v_lshlrev_b32_e32 v176, 16, v216
	v_and_b32_e32 v177, 0xffff0000, v216
	s_waitcnt vmcnt(8)
	v_lshlrev_b32_e32 v178, 16, v220
	v_and_b32_e32 v179, 0xffff0000, v220
	v_lshlrev_b32_e32 v112, 16, v217
	v_and_b32_e32 v113, 0xffff0000, v217
	v_lshlrev_b32_e32 v116, 16, v221
	v_and_b32_e32 v117, 0xffff0000, v221
	v_lshlrev_b32_e32 v180, 16, v218
	v_and_b32_e32 v181, 0xffff0000, v218
	v_lshlrev_b32_e32 v182, 16, v222
	v_and_b32_e32 v183, 0xffff0000, v222
	v_lshlrev_b32_e32 v114, 16, v219
	v_and_b32_e32 v115, 0xffff0000, v219
	v_lshlrev_b32_e32 v118, 16, v223
	v_and_b32_e32 v119, 0xffff0000, v223
	v_pk_fma_f32 v[108:109], v[108:109], v[176:177], v[178:179]
	v_pk_fma_f32 v[110:111], v[110:111], v[112:113], v[116:117]
	v_pk_fma_f32 v[112:113], v[104:105], v[180:181], v[182:183]
	v_pk_fma_f32 v[114:115], v[106:107], v[114:115], v[118:119]
	v_cvt_pk_bf16_f32 v104, v108, v109
	v_cvt_pk_bf16_f32 v105, v110, v111
	v_cvt_pk_bf16_f32 v106, v112, v113
	v_cvt_pk_bf16_f32 v107, v114, v115
	global_store_dwordx4 v[124:125], v[104:107], off
	v_or_b32_e32 v108, 32, v154
	s_waitcnt vmcnt(8)
; __device__ __forceinline__ unsigned pk_bf16(float lo, float hi) { const f32x2 v = {lo, hi}; return __builtin_bit_cast(unsigned, __builtin_convertvector(v, b16x2)); }
;     __device__ __forceinline__ void row(int r, int col32, int fq, const f32x4& a00, const f32x4& a01, const f32x4& a10, const f32x4& a11) const { half(r, col32, fq, a00, a01); half(r, col32 + HALF, fq, a10, a11); }
;     __device__ __forceinline__ void row(int r, int col32, int fq, const f32x4& a00, const f32x4& a01, const f32x4& a10, const f32x4& a11) const { half(r, col32, fq, a00, a01); half(r, col32 + HALF, fq, a10, a11); }
;     ...
;             const int brow = cur.pm * BM, bcol = cur.pn * BM;
; #pragma unroll
;             for (int ai = 0; ai < 2; ++ai)
; #pragma unroll
;                 for (int m = 0; m < 4; ++m) {
;                     E.row(brow + ai * HALF + wr * 64 + m * 16 + fr, bcol + wc * 32, fq, acc[ai][0][m][0], acc[ai][0][m][1], acc[ai][1][m][0], acc[ai][1][m][1]);
;                     asm volatile("" ::: "memory");
;                 }
;     __device__ __forceinline__ void half(int row, int col32, int fq, const f32x4& v0, const f32x4& v1) const {
;         const int col = col32 + 8 * fq;
;         float g[8], a[8]; bf8_to_f(*(const u32x4*)(gates + (size_t)row * 2048 + 1024 + col), g); bf8_to_f(*(const u32x4*)(t1 + (size_t)row * D + col), a);
;         u32x4 w; w.x = pk_bf16(a[0] + v0[0] * g[0], a[1] + v0[1] * g[1]); w.y = pk_bf16(a[2] + v0[2] * g[2], a[3] + v0[3] * g[3]);
;         w.z = pk_bf16(a[4] + v1[0] * g[4], a[5] + v1[1] * g[5]); w.w = pk_bf16(a[6] + v1[2] * g[6], a[7] + v1[3] * g[7]);
;         *(u32x4*)(m + (size_t)row * D + col) = w;
;     }
;     __device__ __forceinline__ void row(int r, int col32, int fq, const f32x4& a00, const f32x4& a01, const f32x4& a10, const f32x4& a11) const { half(r, col32, fq, a00, a01); half(r, col32 + HALF, fq, a10, a11); }
	v_lshlrev_b32_e32 v114, 16, v228
	v_and_b32_e32 v115, 0xffff0000, v228
	v_lshlrev_b32_e32 v116, 16, v229
	v_and_b32_e32 v117, 0xffff0000, v229
	v_lshlrev_b32_e32 v118, 16, v230
	v_and_b32_e32 v119, 0xffff0000, v230
	v_lshlrev_b32_e32 v120, 16, v231
	v_and_b32_e32 v121, 0xffff0000, v231
	v_ashrrev_i32_e32 v109, 31, v108
	v_lshlrev_b64 v[110:111], 12, v[108:109]
	v_lshlrev_b64 v[108:109], 11, v[108:109]
	v_lshl_add_u64 v[110:111], s[88:89], 0, v[110:111]
	v_lshl_add_u64 v[112:113], s[8:9], 0, v[108:109]
	v_lshl_add_u64 v[110:111], v[110:111], 0, v[152:153]
	s_waitcnt vmcnt(7)
	v_lshlrev_b32_e32 v122, 16, v232
	v_and_b32_e32 v123, 0xffff0000, v232
	v_lshlrev_b32_e32 v104, 16, v233
	v_and_b32_e32 v105, 0xffff0000, v233
	v_lshlrev_b32_e32 v126, 16, v234
	v_and_b32_e32 v127, 0xffff0000, v234
	v_lshlrev_b32_e32 v106, 16, v235
	v_and_b32_e32 v107, 0xffff0000, v235
	v_add_u32_e32 v236, 0x30, v154
	v_ashrrev_i32_e32 v237, 31, v236
	v_lshlrev_b64 v[238:239], 12, v[236:237]
	v_lshlrev_b64 v[240:241], 11, v[236:237]
	v_lshl_add_u64 v[238:239], s[88:89], 0, v[238:239]
	v_lshl_add_u64 v[240:241], s[8:9], 0, v[240:241]
	v_lshl_add_u64 v[238:239], v[238:239], 0, v[152:153]
	v_lshl_add_u64 v[240:241], v[240:241], 0, v[152:153]
	global_load_dwordx4 v[216:219], v[238:239], off offset:2048
	global_load_dwordx4 v[220:223], v[240:241], off
	global_load_dwordx4 v[228:231], v[240:241], off offset:256
	global_load_dwordx4 v[232:235], v[238:239], off offset:2304
	s_nop 0
	v_pk_fma_f32 v[100:101], v[100:101], v[122:123], v[114:115]
	v_pk_fma_f32 v[102:103], v[102:103], v[104:105], v[116:117]
	v_pk_fma_f32 v[104:105], v[96:97], v[126:127], v[118:119]
	v_pk_fma_f32 v[106:107], v[98:99], v[106:107], v[120:121]
	v_cvt_pk_bf16_f32 v96, v100, v101
	v_cvt_pk_bf16_f32 v97, v102, v103
	v_cvt_pk_bf16_f32 v98, v104, v105
	v_cvt_pk_bf16_f32 v99, v106, v107
	global_store_dwordx4 v[124:125], v[96:99], off offset:256
	v_lshl_add_u64 v[104:105], v[112:113], 0, v[152:153]
	v_lshl_add_u64 v[106:107], s[10:11], 0, v[108:109]
	v_lshl_add_u64 v[108:109], v[106:107], 0, v[152:153]
	s_waitcnt vmcnt(10)
	v_lshlrev_b32_e32 v112, 16, v200
	v_and_b32_e32 v113, 0xffff0000, v200
	s_waitcnt vmcnt(9)
	v_lshlrev_b32_e32 v114, 16, v204
	v_and_b32_e32 v115, 0xffff0000, v204
	v_lshlrev_b32_e32 v96, 16, v201
	v_and_b32_e32 v97, 0xffff0000, v201
	v_lshlrev_b32_e32 v100, 16, v205
	v_and_b32_e32 v101, 0xffff0000, v205
	v_lshlrev_b32_e32 v116, 16, v202
	v_and_b32_e32 v117, 0xffff0000, v202
	v_lshlrev_b32_e32 v118, 16, v206
	v_and_b32_e32 v119, 0xffff0000, v206
	v_lshlrev_b32_e32 v98, 16, v203
	v_and_b32_e32 v99, 0xffff0000, v203
	v_lshlrev_b32_e32 v102, 16, v207
	v_and_b32_e32 v103, 0xffff0000, v207
	v_pk_fma_f32 v[92:93], v[92:93], v[112:113], v[114:115]
	v_pk_fma_f32 v[94:95], v[94:95], v[96:97], v[100:101]
	v_pk_fma_f32 v[96:97], v[88:89], v[116:117], v[118:119]
	v_pk_fma_f32 v[98:99], v[90:91], v[98:99], v[102:103]
	v_cvt_pk_bf16_f32 v88, v92, v93
	v_cvt_pk_bf16_f32 v89, v94, v95
	v_cvt_pk_bf16_f32 v90, v96, v97
	v_cvt_pk_bf16_f32 v91, v98, v99
	global_store_dwordx4 v[108:109], v[88:91], off
	v_or_b32_e32 v92, 48, v154
	s_waitcnt vmcnt(9)
	v_lshlrev_b32_e32 v98, 16, v208
	v_and_b32_e32 v99, 0xffff0000, v208
	v_lshlrev_b32_e32 v100, 16, v209
	v_and_b32_e32 v101, 0xffff0000, v209
	v_lshlrev_b32_e32 v102, 16, v210
	v_and_b32_e32 v103, 0xffff0000, v210
	v_lshlrev_b32_e32 v104, 16, v211
	v_and_b32_e32 v105, 0xffff0000, v211
	v_ashrrev_i32_e32 v93, 31, v92
	v_lshlrev_b64 v[94:95], 12, v[92:93]
	v_lshlrev_b64 v[92:93], 11, v[92:93]
	v_lshl_add_u64 v[94:95], s[88:89], 0, v[94:95]
	v_lshl_add_u64 v[96:97], s[8:9], 0, v[92:93]
	v_lshl_add_u64 v[94:95], v[94:95], 0, v[152:153]
	s_waitcnt vmcnt(8)
	v_lshlrev_b32_e32 v106, 16, v212
	v_and_b32_e32 v107, 0xffff0000, v212
	v_lshlrev_b32_e32 v88, 16, v213
	v_and_b32_e32 v89, 0xffff0000, v213
	v_lshlrev_b32_e32 v110, 16, v214
	v_and_b32_e32 v111, 0xffff0000, v214
	v_lshlrev_b32_e32 v90, 16, v215
	v_and_b32_e32 v91, 0xffff0000, v215
	v_add_u32_e32 v236, 0x80, v154
	v_ashrrev_i32_e32 v237, 31, v236
	v_lshlrev_b64 v[238:239], 12, v[236:237]
	v_lshlrev_b64 v[240:241], 11, v[236:237]
	v_lshl_add_u64 v[238:239], s[88:89], 0, v[238:239]
	v_lshl_add_u64 v[240:241], s[8:9], 0, v[240:241]
	v_lshl_add_u64 v[238:239], v[238:239], 0, v[152:153]
	v_lshl_add_u64 v[240:241], v[240:241], 0, v[152:153]
	global_load_dwordx4 v[200:203], v[238:239], off offset:2048
	global_load_dwordx4 v[204:207], v[240:241], off
	global_load_dwordx4 v[208:211], v[240:241], off offset:256
	global_load_dwordx4 v[212:215], v[238:239], off offset:2304
	s_nop 0
	v_pk_fma_f32 v[84:85], v[84:85], v[106:107], v[98:99]
	v_pk_fma_f32 v[86:87], v[86:87], v[88:89], v[100:101]
	v_pk_fma_f32 v[88:89], v[80:81], v[110:111], v[102:103]
	v_pk_fma_f32 v[90:91], v[82:83], v[90:91], v[104:105]
	v_cvt_pk_bf16_f32 v80, v84, v85
	v_cvt_pk_bf16_f32 v81, v86, v87
	v_cvt_pk_bf16_f32 v82, v88, v89
	v_cvt_pk_bf16_f32 v83, v90, v91
	global_store_dwordx4 v[108:109], v[80:83], off offset:256
	v_lshl_add_u64 v[88:89], v[96:97], 0, v[152:153]
	v_lshl_add_u64 v[90:91], s[10:11], 0, v[92:93]
	v_lshl_add_u64 v[92:93], v[90:91], 0, v[152:153]
	s_waitcnt vmcnt(10)
	v_lshlrev_b32_e32 v96, 16, v216
	v_and_b32_e32 v97, 0xffff0000, v216
	s_waitcnt vmcnt(9)
; __device__ __forceinline__ unsigned pk_bf16(float lo, float hi) { const f32x2 v = {lo, hi}; return __builtin_bit_cast(unsigned, __builtin_convertvector(v, b16x2)); }
;     __device__ __forceinline__ void row(int r, int col32, int fq, const f32x4& a00, const f32x4& a01, const f32x4& a10, const f32x4& a11) const { half(r, col32, fq, a00, a01); half(r, col32 + HALF, fq, a10, a11); }
;     __device__ __forceinline__ void row(int r, int col32, int fq, const f32x4& a00, const f32x4& a01, const f32x4& a10, const f32x4& a11) const { half(r, col32, fq, a00, a01); half(r, col32 + HALF, fq, a10, a11); }
;     ...
;             const int brow = cur.pm * BM, bcol = cur.pn * BM;
; #pragma unroll
;             for (int ai = 0; ai < 2; ++ai)
; #pragma unroll
;                 for (int m = 0; m < 4; ++m) {
;                     E.row(brow + ai * HALF + wr * 64 + m * 16 + fr, bcol + wc * 32, fq, acc[ai][0][m][0], acc[ai][0][m][1], acc[ai][1][m][0], acc[ai][1][m][1]);
;                     asm volatile("" ::: "memory");
;                 }
;     __device__ __forceinline__ void half(int row, int col32, int fq, const f32x4& v0, const f32x4& v1) const {
;         const int col = col32 + 8 * fq;
;         float g[8], a[8]; bf8_to_f(*(const u32x4*)(gates + (size_t)row * 2048 + 1024 + col), g); bf8_to_f(*(const u32x4*)(t1 + (size_t)row * D + col), a);
;         u32x4 w; w.x = pk_bf16(a[0] + v0[0] * g[0], a[1] + v0[1] * g[1]); w.y = pk_bf16(a[2] + v0[2] * g[2], a[3] + v0[3] * g[3]);
;         w.z = pk_bf16(a[4] + v1[0] * g[4], a[5] + v1[1] * g[5]); w.w = pk_bf16(a[6] + v1[2] * g[6], a[7] + v1[3] * g[7]);
;         *(u32x4*)(m + (size_t)row * D + col) = w;
;     }
;     __device__ __forceinline__ void row(int r, int col32, int fq, const f32x4& a00, const f32x4& a01, const f32x4& a10, const f32x4& a11) const { half(r, col32, fq, a00, a01); half(r, col32 + HALF, fq, a10, a11); }
	v_lshlrev_b32_e32 v98, 16, v220
	v_and_b32_e32 v99, 0xffff0000, v220
	v_lshlrev_b32_e32 v80, 16, v217
	v_and_b32_e32 v81, 0xffff0000, v217
	v_lshlrev_b32_e32 v84, 16, v221
	v_and_b32_e32 v85, 0xffff0000, v221
	v_lshlrev_b32_e32 v100, 16, v218
	v_and_b32_e32 v101, 0xffff0000, v218
	v_lshlrev_b32_e32 v102, 16, v222
	v_and_b32_e32 v103, 0xffff0000, v222
	v_lshlrev_b32_e32 v82, 16, v219
	v_and_b32_e32 v83, 0xffff0000, v219
	v_lshlrev_b32_e32 v86, 16, v223
	v_and_b32_e32 v87, 0xffff0000, v223
	v_pk_fma_f32 v[76:77], v[76:77], v[96:97], v[98:99]
	v_pk_fma_f32 v[78:79], v[78:79], v[80:81], v[84:85]
	v_pk_fma_f32 v[80:81], v[72:73], v[100:101], v[102:103]
	v_pk_fma_f32 v[82:83], v[74:75], v[82:83], v[86:87]
	v_cvt_pk_bf16_f32 v72, v76, v77
	v_cvt_pk_bf16_f32 v73, v78, v79
	v_cvt_pk_bf16_f32 v74, v80, v81
	v_cvt_pk_bf16_f32 v75, v82, v83
	global_store_dwordx4 v[92:93], v[72:75], off
	v_add_u32_e32 v76, 0x80, v154
	s_waitcnt vmcnt(9)
	v_lshlrev_b32_e32 v82, 16, v228
	v_and_b32_e32 v83, 0xffff0000, v228
	v_lshlrev_b32_e32 v84, 16, v229
	v_and_b32_e32 v85, 0xffff0000, v229
	v_lshlrev_b32_e32 v86, 16, v230
	v_and_b32_e32 v87, 0xffff0000, v230
	v_lshlrev_b32_e32 v88, 16, v231
	v_and_b32_e32 v89, 0xffff0000, v231
	v_ashrrev_i32_e32 v77, 31, v76
	v_lshlrev_b64 v[78:79], 12, v[76:77]
	v_lshlrev_b64 v[76:77], 11, v[76:77]
	v_lshl_add_u64 v[78:79], s[88:89], 0, v[78:79]
	v_lshl_add_u64 v[80:81], s[8:9], 0, v[76:77]
	v_lshl_add_u64 v[78:79], v[78:79], 0, v[152:153]
	s_waitcnt vmcnt(8)
	v_lshlrev_b32_e32 v90, 16, v232
	v_and_b32_e32 v91, 0xffff0000, v232
	v_lshlrev_b32_e32 v72, 16, v233
	v_and_b32_e32 v73, 0xffff0000, v233
	v_lshlrev_b32_e32 v94, 16, v234
	v_and_b32_e32 v95, 0xffff0000, v234
	v_lshlrev_b32_e32 v74, 16, v235
	v_and_b32_e32 v75, 0xffff0000, v235
	v_add_u32_e32 v236, 0x90, v154
	v_ashrrev_i32_e32 v237, 31, v236
	v_lshlrev_b64 v[238:239], 12, v[236:237]
	v_lshlrev_b64 v[240:241], 11, v[236:237]
	v_lshl_add_u64 v[238:239], s[88:89], 0, v[238:239]
	v_lshl_add_u64 v[240:241], s[8:9], 0, v[240:241]
	v_lshl_add_u64 v[238:239], v[238:239], 0, v[152:153]
	v_lshl_add_u64 v[240:241], v[240:241], 0, v[152:153]
	global_load_dwordx4 v[216:219], v[238:239], off offset:2048
	global_load_dwordx4 v[220:223], v[240:241], off
	global_load_dwordx4 v[228:231], v[240:241], off offset:256
	global_load_dwordx4 v[232:235], v[238:239], off offset:2304
	s_nop 0
	v_pk_fma_f32 v[68:69], v[68:69], v[90:91], v[82:83]
	v_pk_fma_f32 v[70:71], v[70:71], v[72:73], v[84:85]
	v_pk_fma_f32 v[72:73], v[64:65], v[94:95], v[86:87]
	v_pk_fma_f32 v[74:75], v[66:67], v[74:75], v[88:89]
	v_cvt_pk_bf16_f32 v64, v68, v69
	v_cvt_pk_bf16_f32 v65, v70, v71
	v_cvt_pk_bf16_f32 v66, v72, v73
	v_cvt_pk_bf16_f32 v67, v74, v75
	global_store_dwordx4 v[92:93], v[64:67], off offset:256
	v_lshl_add_u64 v[72:73], v[80:81], 0, v[152:153]
	v_lshl_add_u64 v[74:75], s[10:11], 0, v[76:77]
	v_lshl_add_u64 v[76:77], v[74:75], 0, v[152:153]
	s_waitcnt vmcnt(10)
	v_lshlrev_b32_e32 v80, 16, v200
	v_and_b32_e32 v81, 0xffff0000, v200
	s_waitcnt vmcnt(9)
	v_lshlrev_b32_e32 v82, 16, v204
	v_and_b32_e32 v83, 0xffff0000, v204
	v_lshlrev_b32_e32 v64, 16, v201
	v_and_b32_e32 v65, 0xffff0000, v201
	v_lshlrev_b32_e32 v68, 16, v205
	v_and_b32_e32 v69, 0xffff0000, v205
	v_lshlrev_b32_e32 v84, 16, v202
	v_and_b32_e32 v85, 0xffff0000, v202
	v_lshlrev_b32_e32 v86, 16, v206
	v_and_b32_e32 v87, 0xffff0000, v206
	v_lshlrev_b32_e32 v66, 16, v203
	v_and_b32_e32 v67, 0xffff0000, v203
	v_lshlrev_b32_e32 v70, 16, v207
	v_and_b32_e32 v71, 0xffff0000, v207
	v_pk_fma_f32 v[60:61], v[60:61], v[80:81], v[82:83]
	v_pk_fma_f32 v[62:63], v[62:63], v[64:65], v[68:69]
	v_pk_fma_f32 v[64:65], v[56:57], v[84:85], v[86:87]
	v_pk_fma_f32 v[66:67], v[58:59], v[66:67], v[70:71]
	v_cvt_pk_bf16_f32 v56, v60, v61
	v_cvt_pk_bf16_f32 v57, v62, v63
	v_cvt_pk_bf16_f32 v58, v64, v65
	v_cvt_pk_bf16_f32 v59, v66, v67
	global_store_dwordx4 v[76:77], v[56:59], off
	v_add_u32_e32 v60, 0x90, v154
	s_waitcnt vmcnt(9)
	v_lshlrev_b32_e32 v66, 16, v208
	v_and_b32_e32 v67, 0xffff0000, v208
	v_lshlrev_b32_e32 v68, 16, v209
	v_and_b32_e32 v69, 0xffff0000, v209
	v_lshlrev_b32_e32 v70, 16, v210
	v_and_b32_e32 v71, 0xffff0000, v210
	v_lshlrev_b32_e32 v72, 16, v211
	v_and_b32_e32 v73, 0xffff0000, v211
	v_ashrrev_i32_e32 v61, 31, v60
	v_lshlrev_b64 v[62:63], 12, v[60:61]
	v_lshlrev_b64 v[60:61], 11, v[60:61]
	v_lshl_add_u64 v[62:63], s[88:89], 0, v[62:63]
	v_lshl_add_u64 v[64:65], s[8:9], 0, v[60:61]
	v_lshl_add_u64 v[62:63], v[62:63], 0, v[152:153]
	s_waitcnt vmcnt(8)
	v_lshlrev_b32_e32 v74, 16, v212
	v_and_b32_e32 v75, 0xffff0000, v212
	v_lshlrev_b32_e32 v56, 16, v213
	v_and_b32_e32 v57, 0xffff0000, v213
	v_lshlrev_b32_e32 v78, 16, v214
	v_and_b32_e32 v79, 0xffff0000, v214
	v_lshlrev_b32_e32 v58, 16, v215
	v_and_b32_e32 v59, 0xffff0000, v215
	v_add_u32_e32 v236, 0xa0, v154
	v_ashrrev_i32_e32 v237, 31, v236
	v_lshlrev_b64 v[238:239], 12, v[236:237]
	v_lshlrev_b64 v[240:241], 11, v[236:237]
	v_lshl_add_u64 v[238:239], s[88:89], 0, v[238:239]
	v_lshl_add_u64 v[240:241], s[8:9], 0, v[240:241]
	v_lshl_add_u64 v[238:239], v[238:239], 0, v[152:153]
	v_lshl_add_u64 v[240:241], v[240:241], 0, v[152:153]
	global_load_dwordx4 v[200:203], v[238:239], off offset:2048
	global_load_dwordx4 v[204:207], v[240:241], off
	global_load_dwordx4 v[208:211], v[240:241], off offset:256
	global_load_dwordx4 v[212:215], v[238:239], off offset:2304
	s_nop 0
	v_pk_fma_f32 v[52:53], v[52:53], v[74:75], v[66:67]
	v_pk_fma_f32 v[54:55], v[54:55], v[56:57], v[68:69]
	v_pk_fma_f32 v[56:57], v[48:49], v[78:79], v[70:71]
	v_pk_fma_f32 v[58:59], v[50:51], v[58:59], v[72:73]
	v_cvt_pk_bf16_f32 v48, v52, v53
	v_cvt_pk_bf16_f32 v49, v54, v55
	v_cvt_pk_bf16_f32 v50, v56, v57
	v_cvt_pk_bf16_f32 v51, v58, v59
	global_store_dwordx4 v[76:77], v[48:51], off offset:256
	v_lshl_add_u64 v[56:57], v[64:65], 0, v[152:153]
	v_lshl_add_u64 v[58:59], s[10:11], 0, v[60:61]
	v_lshl_add_u64 v[60:61], v[58:59], 0, v[152:153]
	s_waitcnt vmcnt(10)
; __device__ __forceinline__ unsigned pk_bf16(float lo, float hi) { const f32x2 v = {lo, hi}; return __builtin_bit_cast(unsigned, __builtin_convertvector(v, b16x2)); }
;     __device__ __forceinline__ void row(int r, int col32, int fq, const f32x4& a00, const f32x4& a01, const f32x4& a10, const f32x4& a11) const { half(r, col32, fq, a00, a01); half(r, col32 + HALF, fq, a10, a11); }
;     __device__ __forceinline__ void row(int r, int col32, int fq, const f32x4& a00, const f32x4& a01, const f32x4& a10, const f32x4& a11) const { half(r, col32, fq, a00, a01); half(r, col32 + HALF, fq, a10, a11); }
;     ...
;             const int brow = cur.pm * BM, bcol = cur.pn * BM;
; #pragma unroll
;             for (int ai = 0; ai < 2; ++ai)
; #pragma unroll
;                 for (int m = 0; m < 4; ++m) {
;                     E.row(brow + ai * HALF + wr * 64 + m * 16 + fr, bcol + wc * 32, fq, acc[ai][0][m][0], acc[ai][0][m][1], acc[ai][1][m][0], acc[ai][1][m][1]);
;                     asm volatile("" ::: "memory");
;                 }
;     __device__ __forceinline__ void half(int row, int col32, int fq, const f32x4& v0, const f32x4& v1) const {
;         const int col = col32 + 8 * fq;
;         float g[8], a[8]; bf8_to_f(*(const u32x4*)(gates + (size_t)row * 2048 + 1024 + col), g); bf8_to_f(*(const u32x4*)(t1 + (size_t)row * D + col), a);
;         u32x4 w; w.x = pk_bf16(a[0] + v0[0] * g[0], a[1] + v0[1] * g[1]); w.y = pk_bf16(a[2] + v0[2] * g[2], a[3] + v0[3] * g[3]);
;         w.z = pk_bf16(a[4] + v1[0] * g[4], a[5] + v1[1] * g[5]); w.w = pk_bf16(a[6] + v1[2] * g[6], a[7] + v1[3] * g[7]);
;         *(u32x4*)(m + (size_t)row * D + col) = w;
;     }
;     __device__ __forceinline__ void row(int r, int col32, int fq, const f32x4& a00, const f32x4& a01, const f32x4& a10, const f32x4& a11) const { half(r, col32, fq, a00, a01); half(r, col32 + HALF, fq, a10, a11); }
	v_lshlrev_b32_e32 v64, 16, v216
	v_and_b32_e32 v65, 0xffff0000, v216
	s_waitcnt vmcnt(9)
	v_lshlrev_b32_e32 v66, 16, v220
	v_and_b32_e32 v67, 0xffff0000, v220
	v_lshlrev_b32_e32 v48, 16, v217
	v_and_b32_e32 v49, 0xffff0000, v217
	v_lshlrev_b32_e32 v52, 16, v221
	v_and_b32_e32 v53, 0xffff0000, v221
	v_lshlrev_b32_e32 v68, 16, v218
	v_and_b32_e32 v69, 0xffff0000, v218
	v_lshlrev_b32_e32 v70, 16, v222
	v_and_b32_e32 v71, 0xffff0000, v222
	v_lshlrev_b32_e32 v50, 16, v219
	v_and_b32_e32 v51, 0xffff0000, v219
	v_lshlrev_b32_e32 v54, 16, v223
	v_and_b32_e32 v55, 0xffff0000, v223
	v_pk_fma_f32 v[44:45], v[44:45], v[64:65], v[66:67]
	v_pk_fma_f32 v[46:47], v[46:47], v[48:49], v[52:53]
	v_pk_fma_f32 v[48:49], v[40:41], v[68:69], v[70:71]
	v_pk_fma_f32 v[50:51], v[42:43], v[50:51], v[54:55]
	v_cvt_pk_bf16_f32 v40, v44, v45
	v_cvt_pk_bf16_f32 v41, v46, v47
	v_cvt_pk_bf16_f32 v42, v48, v49
	v_cvt_pk_bf16_f32 v43, v50, v51
	global_store_dwordx4 v[60:61], v[40:43], off
	v_add_u32_e32 v44, 0xa0, v154
	s_waitcnt vmcnt(9)
	v_lshlrev_b32_e32 v50, 16, v228
	v_and_b32_e32 v51, 0xffff0000, v228
	v_lshlrev_b32_e32 v52, 16, v229
	v_and_b32_e32 v53, 0xffff0000, v229
	v_lshlrev_b32_e32 v54, 16, v230
	v_and_b32_e32 v55, 0xffff0000, v230
	v_lshlrev_b32_e32 v56, 16, v231
	v_and_b32_e32 v57, 0xffff0000, v231
	v_ashrrev_i32_e32 v45, 31, v44
	v_lshlrev_b64 v[46:47], 12, v[44:45]
	v_lshlrev_b64 v[44:45], 11, v[44:45]
	v_lshl_add_u64 v[46:47], s[88:89], 0, v[46:47]
	v_lshl_add_u64 v[48:49], s[8:9], 0, v[44:45]
	v_lshl_add_u64 v[46:47], v[46:47], 0, v[152:153]
	s_waitcnt vmcnt(8)
	v_lshlrev_b32_e32 v58, 16, v232
	v_and_b32_e32 v59, 0xffff0000, v232
	v_lshlrev_b32_e32 v40, 16, v233
	v_and_b32_e32 v41, 0xffff0000, v233
	v_lshlrev_b32_e32 v62, 16, v234
	v_and_b32_e32 v63, 0xffff0000, v234
	v_lshlrev_b32_e32 v42, 16, v235
	v_and_b32_e32 v43, 0xffff0000, v235
	v_add_u32_e32 v236, 0xb0, v154
	v_ashrrev_i32_e32 v237, 31, v236
	v_lshlrev_b64 v[238:239], 12, v[236:237]
	v_lshlrev_b64 v[240:241], 11, v[236:237]
	v_lshl_add_u64 v[238:239], s[88:89], 0, v[238:239]
	v_lshl_add_u64 v[240:241], s[8:9], 0, v[240:241]
	v_lshl_add_u64 v[238:239], v[238:239], 0, v[152:153]
	v_lshl_add_u64 v[240:241], v[240:241], 0, v[152:153]
	global_load_dwordx4 v[216:219], v[238:239], off offset:2048
	global_load_dwordx4 v[220:223], v[240:241], off
	global_load_dwordx4 v[228:231], v[240:241], off offset:256
	global_load_dwordx4 v[232:235], v[238:239], off offset:2304
	s_nop 0
	v_pk_fma_f32 v[36:37], v[36:37], v[58:59], v[50:51]
	v_pk_fma_f32 v[38:39], v[38:39], v[40:41], v[52:53]
	v_pk_fma_f32 v[40:41], v[32:33], v[62:63], v[54:55]
	v_pk_fma_f32 v[42:43], v[34:35], v[42:43], v[56:57]
	v_cvt_pk_bf16_f32 v32, v36, v37
	v_cvt_pk_bf16_f32 v33, v38, v39
	v_cvt_pk_bf16_f32 v34, v40, v41
	v_cvt_pk_bf16_f32 v35, v42, v43
	global_store_dwordx4 v[60:61], v[32:35], off offset:256
	v_lshl_add_u64 v[40:41], v[48:49], 0, v[152:153]
	v_lshl_add_u64 v[42:43], s[10:11], 0, v[44:45]
	v_lshl_add_u64 v[44:45], v[42:43], 0, v[152:153]
	s_waitcnt vmcnt(10)
	v_lshlrev_b32_e32 v48, 16, v200
	v_and_b32_e32 v49, 0xffff0000, v200
	s_waitcnt vmcnt(9)
	v_lshlrev_b32_e32 v50, 16, v204
	v_and_b32_e32 v51, 0xffff0000, v204
	v_lshlrev_b32_e32 v32, 16, v201
	v_and_b32_e32 v33, 0xffff0000, v201
	v_lshlrev_b32_e32 v36, 16, v205
	v_and_b32_e32 v37, 0xffff0000, v205
	v_lshlrev_b32_e32 v52, 16, v202
	v_and_b32_e32 v53, 0xffff0000, v202
	v_lshlrev_b32_e32 v54, 16, v206
	v_and_b32_e32 v55, 0xffff0000, v206
	v_lshlrev_b32_e32 v34, 16, v203
	v_and_b32_e32 v35, 0xffff0000, v203
	v_lshlrev_b32_e32 v38, 16, v207
	v_and_b32_e32 v39, 0xffff0000, v207
	v_pk_fma_f32 v[28:29], v[28:29], v[48:49], v[50:51]
	v_pk_fma_f32 v[30:31], v[30:31], v[32:33], v[36:37]
	v_pk_fma_f32 v[32:33], v[24:25], v[52:53], v[54:55]
	v_pk_fma_f32 v[34:35], v[26:27], v[34:35], v[38:39]
	v_cvt_pk_bf16_f32 v24, v28, v29
	v_cvt_pk_bf16_f32 v25, v30, v31
	v_cvt_pk_bf16_f32 v26, v32, v33
	v_cvt_pk_bf16_f32 v27, v34, v35
	global_store_dwordx4 v[44:45], v[24:27], off
	v_add_u32_e32 v28, 0xb0, v154
	s_waitcnt vmcnt(9)
; __device__ __forceinline__ unsigned pk_bf16(float lo, float hi) { const f32x2 v = {lo, hi}; return __builtin_bit_cast(unsigned, __builtin_convertvector(v, b16x2)); }
;     __device__ __forceinline__ void row(int r, int col32, int fq, const f32x4& a00, const f32x4& a01, const f32x4& a10, const f32x4& a11) const { half(r, col32, fq, a00, a01); half(r, col32 + HALF, fq, a10, a11); }
;     __device__ __forceinline__ void row(int r, int col32, int fq, const f32x4& a00, const f32x4& a01, const f32x4& a10, const f32x4& a11) const { half(r, col32, fq, a00, a01); half(r, col32 + HALF, fq, a10, a11); }
;     ...
;             const int brow = cur.pm * BM, bcol = cur.pn * BM;
; #pragma unroll
;             for (int ai = 0; ai < 2; ++ai)
; #pragma unroll
;                 for (int m = 0; m < 4; ++m) {
;                     E.row(brow + ai * HALF + wr * 64 + m * 16 + fr, bcol + wc * 32, fq, acc[ai][0][m][0], acc[ai][0][m][1], acc[ai][1][m][0], acc[ai][1][m][1]);
;                     asm volatile("" ::: "memory");
;                 }
;     __device__ __forceinline__ void half(int row, int col32, int fq, const f32x4& v0, const f32x4& v1) const {
;         const int col = col32 + 8 * fq;
;         float g[8], a[8]; bf8_to_f(*(const u32x4*)(gates + (size_t)row * 2048 + 1024 + col), g); bf8_to_f(*(const u32x4*)(t1 + (size_t)row * D + col), a);
;         u32x4 w; w.x = pk_bf16(a[0] + v0[0] * g[0], a[1] + v0[1] * g[1]); w.y = pk_bf16(a[2] + v0[2] * g[2], a[3] + v0[3] * g[3]);
;         w.z = pk_bf16(a[4] + v1[0] * g[4], a[5] + v1[1] * g[5]); w.w = pk_bf16(a[6] + v1[2] * g[6], a[7] + v1[3] * g[7]);
;         *(u32x4*)(m + (size_t)row * D + col) = w;
;     }
;     __device__ __forceinline__ void row(int r, int col32, int fq, const f32x4& a00, const f32x4& a01, const f32x4& a10, const f32x4& a11) const { half(r, col32, fq, a00, a01); half(r, col32 + HALF, fq, a10, a11); }
	v_lshlrev_b32_e32 v34, 16, v208
	v_and_b32_e32 v35, 0xffff0000, v208
	v_lshlrev_b32_e32 v36, 16, v209
	v_and_b32_e32 v37, 0xffff0000, v209
	v_lshlrev_b32_e32 v38, 16, v210
	v_and_b32_e32 v39, 0xffff0000, v210
	v_lshlrev_b32_e32 v40, 16, v211
	v_and_b32_e32 v41, 0xffff0000, v211
	v_ashrrev_i32_e32 v29, 31, v28
	v_lshlrev_b64 v[30:31], 12, v[28:29]
	v_lshlrev_b64 v[28:29], 11, v[28:29]
	v_lshl_add_u64 v[30:31], s[88:89], 0, v[30:31]
	v_lshl_add_u64 v[32:33], s[8:9], 0, v[28:29]
	v_lshl_add_u64 v[30:31], v[30:31], 0, v[152:153]
	s_waitcnt vmcnt(8)
	v_lshlrev_b32_e32 v42, 16, v212
	v_and_b32_e32 v43, 0xffff0000, v212
	v_lshlrev_b32_e32 v24, 16, v213
	v_and_b32_e32 v25, 0xffff0000, v213
	v_lshlrev_b32_e32 v46, 16, v214
	v_and_b32_e32 v47, 0xffff0000, v214
	v_lshlrev_b32_e32 v26, 16, v215
	v_and_b32_e32 v27, 0xffff0000, v215
	v_pk_fma_f32 v[20:21], v[20:21], v[42:43], v[34:35]
	v_pk_fma_f32 v[22:23], v[22:23], v[24:25], v[36:37]
	v_pk_fma_f32 v[24:25], v[16:17], v[46:47], v[38:39]
	v_pk_fma_f32 v[26:27], v[18:19], v[26:27], v[40:41]
	v_cvt_pk_bf16_f32 v16, v20, v21
	v_cvt_pk_bf16_f32 v17, v22, v23
	v_cvt_pk_bf16_f32 v18, v24, v25
	v_cvt_pk_bf16_f32 v19, v26, v27
	global_store_dwordx4 v[44:45], v[16:19], off offset:256
	v_lshl_add_u64 v[24:25], v[32:33], 0, v[152:153]
	v_lshl_add_u64 v[26:27], s[10:11], 0, v[28:29]
	v_lshl_add_u64 v[28:29], v[26:27], 0, v[152:153]
	s_waitcnt vmcnt(6)
	v_lshlrev_b32_e32 v32, 16, v216
	v_and_b32_e32 v33, 0xffff0000, v216
	s_waitcnt vmcnt(5)
	v_lshlrev_b32_e32 v34, 16, v220
	v_and_b32_e32 v35, 0xffff0000, v220
	v_lshlrev_b32_e32 v16, 16, v217
	v_and_b32_e32 v17, 0xffff0000, v217
	v_lshlrev_b32_e32 v20, 16, v221
	v_and_b32_e32 v21, 0xffff0000, v221
	v_lshlrev_b32_e32 v36, 16, v218
	v_and_b32_e32 v37, 0xffff0000, v218
	v_lshlrev_b32_e32 v38, 16, v222
	v_and_b32_e32 v39, 0xffff0000, v222
	v_lshlrev_b32_e32 v18, 16, v219
	v_and_b32_e32 v19, 0xffff0000, v219
	v_lshlrev_b32_e32 v22, 16, v223
	v_and_b32_e32 v23, 0xffff0000, v223
	v_pk_fma_f32 v[12:13], v[12:13], v[32:33], v[34:35]
	v_pk_fma_f32 v[14:15], v[14:15], v[16:17], v[20:21]
	v_pk_fma_f32 v[16:17], v[8:9], v[36:37], v[38:39]
	v_pk_fma_f32 v[18:19], v[10:11], v[18:19], v[22:23]
	v_cvt_pk_bf16_f32 v8, v12, v13
	v_cvt_pk_bf16_f32 v9, v14, v15
	v_cvt_pk_bf16_f32 v10, v16, v17
	v_cvt_pk_bf16_f32 v11, v18, v19
	global_store_dwordx4 v[28:29], v[8:11], off
	s_waitcnt vmcnt(5)
	v_lshlrev_b32_e32 v12, 16, v228
	v_and_b32_e32 v13, 0xffff0000, v228
	v_lshlrev_b32_e32 v14, 16, v229
	v_and_b32_e32 v15, 0xffff0000, v229
	v_lshlrev_b32_e32 v16, 16, v230
	v_and_b32_e32 v17, 0xffff0000, v230
	v_lshlrev_b32_e32 v18, 16, v231
	v_and_b32_e32 v19, 0xffff0000, v231
	s_waitcnt vmcnt(4)
	v_lshlrev_b32_e32 v20, 16, v232
	v_and_b32_e32 v21, 0xffff0000, v232
	v_lshlrev_b32_e32 v8, 16, v233
	v_and_b32_e32 v9, 0xffff0000, v233
	v_lshlrev_b32_e32 v22, 16, v234
	v_and_b32_e32 v23, 0xffff0000, v234
	v_lshlrev_b32_e32 v10, 16, v235
	v_and_b32_e32 v11, 0xffff0000, v235
	v_pk_fma_f32 v[4:5], v[4:5], v[20:21], v[12:13]
	v_pk_fma_f32 v[6:7], v[6:7], v[8:9], v[14:15]
	v_pk_fma_f32 v[8:9], v[0:1], v[22:23], v[16:17]
	v_pk_fma_f32 v[10:11], v[2:3], v[10:11], v[18:19]
	v_cvt_pk_bf16_f32 v0, v4, v5
	v_cvt_pk_bf16_f32 v1, v6, v7
	v_cvt_pk_bf16_f32 v2, v8, v9
	v_cvt_pk_bf16_f32 v3, v10, v11
	global_store_dwordx4 v[28:29], v[0:3], off offset:256
	s_cbranch_vccnz .LBB0_1039
	s_andn2_b64 vcc, exec, s[0:1]
	s_cbranch_vccnz .LBB0_1038
	s_barrier
	s_branch .LBB0_1038
